# attention tile loop: static s_setprio 1 for waves 4-7 (the SIMD partners of waves 0-3), reset after the loop
# speedup vs baseline: 1.0083x; 1.0053x over previous
; #define LAS __attribute__((address_space(3)))
; #define MFMA32(a, b, c) __builtin_amdgcn_mfma_f32_32x32x16_bf16((a), (b), (c), 0, 0, 0)
; #define DIFF_ISSUE(T_) do { const unsigned sb_ = lbase + (unsigned)((T_) & 3) * 32768u; const bf16* k_ = gk + (size_t)(T_) * (64 * 512); const bf16* v_ = gv + (size_t)(T_) * 64; \
;         glds16(k_, sb_); glds16(k_ + 64, sb_ + 8192u); glds16(v_, sb_ + 16384u); glds16(v_ + (size_t)64 * VPITCH, sb_ + 24576u); } while (0)
; __device__ __forceinline__ void diff_unit_lds(LAS unsigned char* lds, const bf16* Qd, const bf16* Kd, const bf16* VdT, bf16* MIX, const float* ghead, float lam, int head, int u, int wave, int lane) {
;     ...
;     for (int T = 0; T < nT; ++T) {
;         LAS unsigned char* st = lds + (T & 3) * 32768;
;         if ((T & 1) == 0) {
;             asm volatile("s_waitcnt vmcnt(0) lgkmcnt(0)\n\ts_barrier" ::: "memory");
;             if (T + 2 < nT) DIFF_ISSUE(T + 2);
;             if (T + 3 < nT) DIFF_ISSUE(T + 3);
;         }
;         if (T <= Tlast) {
;             const bool part = (T == Tlast);
;             const bool masked = part && (h == 1);
;             f32x16 S0 = NEGM, S1 = NEGM;
; #pragma unroll
;             for (int ds = 0; ds < 4; ++ds) S0 = MFMA32(*(const LAS bf16x8*)(st + koff + (((2 * ds + h) ^ kx) << 4)), qf[ds], S0);
;             if (!part) {
; #pragma unroll
;                 for (int ds = 0; ds < 4; ++ds) S1 = MFMA32(*(const LAS bf16x8*)(st + koff + 4096 + (((2 * ds + h) ^ kx) << 4)), qf[ds], S1);
;             }
;             float tmax = S0[0];
; #pragma unroll
;             for (int i = 1; i < 16; ++i) tmax = fmaxf(tmax, S0[i]);
;             if (masked) tmax = -1e30f;
;             if (!part) {
; #pragma unroll
;                 for (int i = 0; i < 16; ++i) tmax = fmaxf(tmax, S1[i]);
;             }
;             tmax = fmaxf(tmax, xhalf(tmax, h));
;             if (T == 0 || __any(tmax > 8.0f)) {
.Lq_no_t3:
	s_mov_b32 m0, s7
	s_lshl_b32 s93, s56, 1
	s_or_b32 s91, s23, s93
	s_add_i32 s91, s91, 1
	s_lshl_b32 s92, s91, 1
	s_mov_b32 s94, 0
	s_mov_b32 s96, 0xff800000
	s_mov_b32 s97, 0xff800000
	s_mov_b32 s59, 0
	v_mov_b32_e32 v66, 0
	v_mov_b32_e32 v67, 0
	v_mov_b32_e32 v68, 0
	v_mov_b32_e32 v69, 0
	v_mov_b32_e32 v70, 0
	v_mov_b32_e32 v71, 0
	v_mov_b32_e32 v72, 0
	v_mov_b32_e32 v73, 0
	v_mov_b32_e32 v74, 0
	v_mov_b32_e32 v75, 0
	v_mov_b32_e32 v76, 0
	v_mov_b32_e32 v77, 0
	v_mov_b32_e32 v78, 0
	v_mov_b32_e32 v79, 0
	v_mov_b32_e32 v80, 0
	v_mov_b32_e32 v81, 0
	v_mov_b32_e32 v219, 0
	v_mov_b32_e32 v82, 0
	v_mov_b32_e32 v83, 0
	v_mov_b32_e32 v84, 0
	v_mov_b32_e32 v85, 0
	v_mov_b32_e32 v86, 0
	v_mov_b32_e32 v87, 0
	v_mov_b32_e32 v88, 0
	v_mov_b32_e32 v89, 0
	v_mov_b32_e32 v220, 0
	v_mov_b32_e32 v221, 0
	v_mov_b32_e32 v222, 0
	v_mov_b32_e32 v223, 0
	v_mov_b32_e32 v226, 0
	v_mov_b32_e32 v227, 0
	v_mov_b32_e32 v228, 0
	v_mov_b32_e32 v229, 0
	v_mov_b32_e32 v230, 0
	v_mov_b32_e32 v231, 0
	v_mov_b32_e32 v232, 0
	v_mov_b32_e32 v233, 0
	v_mov_b32_e32 v234, 0
	v_mov_b32_e32 v235, 0
	v_mov_b32_e32 v236, 0
	v_mov_b32_e32 v237, 0
	v_mov_b32_e32 v238, 0
	v_mov_b32_e32 v239, 0
	v_mov_b32_e32 v240, 0
	v_mov_b32_e32 v241, 0
	v_mov_b32_e32 v242, 0
	v_mov_b32_e32 v243, 0
	v_mov_b32_e32 v244, 0
	v_mov_b32_e32 v245, 0
	v_mov_b32_e32 v246, 0
	v_mov_b32_e32 v247, 0
	v_mov_b32_e32 v248, 0
	v_mov_b32_e32 v249, 0
	v_mov_b32_e32 v252, 0
	v_mov_b32_e32 v253, 0
	v_mov_b32_e32 v254, 0
	v_mov_b32_e32 v255, 0
	v_mov_b32_e32 v203, v209
	v_mov_b32_e32 v204, v210
	v_mov_b32_e32 v192, v211
	v_mov_b32_e32 v193, v212
	ds_read_b128 v[164:167], v203
	ds_read_b128 v[168:171], v204
	ds_read_b128 v[172:175], v192
	ds_read_b128 v[176:179], v193
	s_waitcnt lgkmcnt(3)
	v_mfma_f32_32x32x16_bf16 v[98:113], v[164:167], v[126:129], v[66:81]
	s_waitcnt lgkmcnt(2)
	v_mfma_f32_32x32x16_bf16 v[98:113], v[168:171], v[122:125], v[98:113]
	s_waitcnt lgkmcnt(1)
	v_mfma_f32_32x32x16_bf16 v[98:113], v[172:175], v[118:121], v[98:113]
	s_waitcnt lgkmcnt(0)
	v_mfma_f32_32x32x16_bf16 v[98:113], v[176:179], v[114:117], v[98:113]
	s_nop 3
	s_cmp_lt_u32 s78, 4
	s_cbranch_scc1 .Lq_prio_done
	s_setprio 1
.Lq_prio_done:
.Lq_even_top:
	s_cmp_eq_u32 s94, s92
	s_cbranch_scc1 .Lq_last
	s_lshr_b32 s0, s94, 1
	s_and_b32 s0, s0, 3
	s_lshl_b32 s95, s0, 15
	ds_read_b128 v[164:167], v203 offset:4096
	ds_read_b128 v[168:171], v204 offset:4096
	ds_read_b128 v[172:175], v192 offset:4096
	ds_read_b128 v[176:179], v193 offset:4096
	v_add_u32_e32 v208, s95, v133
	v_add_u32_e32 v213, s95, v205
	s_waitcnt lgkmcnt(4)
	v_mfma_f32_32x32x16_bf16 v[50:65], v[220:223], v[82:85], v[50:65]
	ds_read_b128 v[220:223], v208 offset:16384
	v_max3_f32 v1, v98, v99, v100
	v_max3_f32 v1, v1, v101, v102
	v_max3_f32 v1, v1, v103, v104
	v_max3_f32 v1, v1, v105, v106
	v_max3_f32 v1, v1, v107, v108
	v_mfma_f32_32x32x16_bf16 v[34:49], v[226:229], v[82:85], v[34:49]
	ds_read_b128 v[226:229], v208 offset:20480
	v_max3_f32 v1, v1, v109, v110
	v_max3_f32 v1, v1, v111, v112
	v_max_f32_e32 v224, v1, v113
	v_max_f32_e32 v225, v1, v113
	v_mfma_f32_32x32x16_bf16 v[18:33], v[230:233], v[82:85], v[18:33]
	ds_read_b128 v[230:233], v208 offset:24576
	s_nop 1
	v_permlane32_swap_b32_e32 v224, v225
	v_max_f32_e32 v1, v224, v225
	v_cmp_lt_f32_e32 vcc, s96, v1
	s_cbranch_vccnz .Lq_re_e

; __device__ __forceinline__ void diff_unit_lds(LAS unsigned char* lds, const bf16* Qd, const bf16* Kd, const bf16* VdT, bf16* MIX, const float* ghead, float lam, int head, int u, int wave, int lane) {
;     ...
;     }
;     ...
;     __syncthreads();
;     const float lsum = l + __shfl_xor(l, 32);
;     diff_combine(lds + 65536, O, lsum, lam, slot, comp, ghead, MIX + (size_t)row * 1024 + head * 128, true);
.Lq_done:
	s_setprio 0
	s_nop 7
	s_branch .LBB0_496
